# residual-add epilogues of the three output-projection GEMM phases keep four reads of x in flight instead of one serial round trip per 16 bytes
# speedup vs baseline: 1.2517x; 1.0038x over previous
.LBB0_1015:
	v_lshl_add_u32 v150, s51, 8, v143
	v_lshl_or_b32 v148, s52, 8, v153
	v_ashrrev_i32_e32 v151, 31, v150
	v_ashrrev_i32_e32 v149, 31, v148
	v_lshlrev_b64 v[140:141], 10, v[150:151]
	v_lshl_add_u64 v[140:141], v[140:141], 0, v[148:149]
	v_lshl_add_u64 v[140:141], v[140:141], 2, s[18:19]
	global_load_dwordx4 v[236:239], v[140:141], off offset:0
	global_load_dwordx4 v[240:243], v[140:141], off offset:16
	global_load_dwordx4 v[244:247], v[140:141], off offset:512
	global_load_dwordx4 v[248:251], v[140:141], off offset:528
	s_waitcnt vmcnt(3)
	v_pk_add_f32 v[128:129], v[128:129], v[238:239]
	v_pk_add_f32 v[126:127], v[126:127], v[236:237]
	global_store_dwordx4 v[140:141], v[126:129], off offset:0
	s_mov_b64 s[0:1], 0x10000
	v_lshl_add_u64 v[252:253], v[140:141], 0, s[0:1]
	global_load_dwordx4 v[236:239], v[252:253], off offset:0
	s_waitcnt vmcnt(4)
	v_pk_add_f32 v[124:125], v[124:125], v[242:243]
	v_pk_add_f32 v[122:123], v[122:123], v[240:241]
	global_store_dwordx4 v[140:141], v[122:125], off offset:16
	global_load_dwordx4 v[240:243], v[252:253], off offset:16
	s_waitcnt vmcnt(5)
	v_pk_add_f32 v[120:121], v[120:121], v[246:247]
	v_pk_add_f32 v[118:119], v[118:119], v[244:245]
	global_store_dwordx4 v[140:141], v[118:121], off offset:512
	global_load_dwordx4 v[244:247], v[252:253], off offset:512
	s_waitcnt vmcnt(6)
	v_pk_add_f32 v[116:117], v[116:117], v[250:251]
	v_pk_add_f32 v[114:115], v[114:115], v[248:249]
	global_store_dwordx4 v[140:141], v[114:117], off offset:528
	global_load_dwordx4 v[248:251], v[252:253], off offset:528
	s_waitcnt vmcnt(6)
	v_pk_add_f32 v[112:113], v[112:113], v[238:239]
	v_pk_add_f32 v[110:111], v[110:111], v[236:237]
	global_store_dwordx4 v[252:253], v[110:113], off offset:0
	s_mov_b64 s[0:1], 0x10000
	v_lshl_add_u64 v[140:141], v[252:253], 0, s[0:1]
	global_load_dwordx4 v[236:239], v[140:141], off offset:0
	s_waitcnt vmcnt(6)
	v_pk_add_f32 v[108:109], v[108:109], v[242:243]
	v_pk_add_f32 v[106:107], v[106:107], v[240:241]
	global_store_dwordx4 v[252:253], v[106:109], off offset:16
	global_load_dwordx4 v[240:243], v[140:141], off offset:16
	s_waitcnt vmcnt(6)
	v_pk_add_f32 v[104:105], v[104:105], v[246:247]
	v_pk_add_f32 v[102:103], v[102:103], v[244:245]
	global_store_dwordx4 v[252:253], v[102:105], off offset:512
	global_load_dwordx4 v[244:247], v[140:141], off offset:512
	s_waitcnt vmcnt(6)
	v_pk_add_f32 v[100:101], v[100:101], v[250:251]
	v_pk_add_f32 v[98:99], v[98:99], v[248:249]
	global_store_dwordx4 v[252:253], v[98:101], off offset:528
	global_load_dwordx4 v[248:251], v[140:141], off offset:528
	s_waitcnt vmcnt(6)
	v_pk_add_f32 v[96:97], v[96:97], v[238:239]
	v_pk_add_f32 v[94:95], v[94:95], v[236:237]
	global_store_dwordx4 v[140:141], v[94:97], off offset:0
	s_mov_b64 s[0:1], 0x10000
	v_lshl_add_u64 v[252:253], v[140:141], 0, s[0:1]
	global_load_dwordx4 v[236:239], v[252:253], off offset:0
	s_waitcnt vmcnt(6)
	v_pk_add_f32 v[92:93], v[92:93], v[242:243]
	v_pk_add_f32 v[90:91], v[90:91], v[240:241]
	global_store_dwordx4 v[140:141], v[90:93], off offset:16
	global_load_dwordx4 v[240:243], v[252:253], off offset:16
	s_waitcnt vmcnt(6)
	v_pk_add_f32 v[88:89], v[88:89], v[246:247]
	v_pk_add_f32 v[86:87], v[86:87], v[244:245]
	global_store_dwordx4 v[140:141], v[86:89], off offset:512
	global_load_dwordx4 v[244:247], v[252:253], off offset:512
	s_waitcnt vmcnt(6)
	v_pk_add_f32 v[84:85], v[84:85], v[250:251]
	v_pk_add_f32 v[82:83], v[82:83], v[248:249]
	global_store_dwordx4 v[140:141], v[82:85], off offset:528
	global_load_dwordx4 v[248:251], v[252:253], off offset:528
	s_waitcnt vmcnt(6)
	v_pk_add_f32 v[80:81], v[80:81], v[238:239]
	v_pk_add_f32 v[78:79], v[78:79], v[236:237]
	global_store_dwordx4 v[252:253], v[78:81], off offset:0
	s_mov_b64 s[0:1], 0x50000
	v_lshl_add_u64 v[140:141], v[252:253], 0, s[0:1]
	global_load_dwordx4 v[236:239], v[140:141], off offset:0
	s_waitcnt vmcnt(6)
	v_pk_add_f32 v[76:77], v[76:77], v[242:243]
	v_pk_add_f32 v[74:75], v[74:75], v[240:241]
	global_store_dwordx4 v[252:253], v[74:77], off offset:16
	global_load_dwordx4 v[240:243], v[140:141], off offset:16
	s_waitcnt vmcnt(6)
	v_pk_add_f32 v[72:73], v[72:73], v[246:247]
	v_pk_add_f32 v[70:71], v[70:71], v[244:245]
	global_store_dwordx4 v[252:253], v[70:73], off offset:512
	global_load_dwordx4 v[244:247], v[140:141], off offset:512
	s_waitcnt vmcnt(6)
	v_pk_add_f32 v[68:69], v[68:69], v[250:251]
	v_pk_add_f32 v[66:67], v[66:67], v[248:249]
	global_store_dwordx4 v[252:253], v[66:69], off offset:528
	global_load_dwordx4 v[248:251], v[140:141], off offset:528
	s_waitcnt vmcnt(6)
	v_pk_add_f32 v[62:63], v[62:63], v[238:239]
	v_pk_add_f32 v[60:61], v[60:61], v[236:237]
	global_store_dwordx4 v[140:141], v[60:63], off offset:0
	s_mov_b64 s[0:1], 0x10000
	v_lshl_add_u64 v[252:253], v[140:141], 0, s[0:1]
	global_load_dwordx4 v[236:239], v[252:253], off offset:0
	s_waitcnt vmcnt(6)
	v_pk_add_f32 v[58:59], v[58:59], v[242:243]
	v_pk_add_f32 v[56:57], v[56:57], v[240:241]
	global_store_dwordx4 v[140:141], v[56:59], off offset:16
	global_load_dwordx4 v[240:243], v[252:253], off offset:16
	s_waitcnt vmcnt(6)
	v_pk_add_f32 v[54:55], v[54:55], v[246:247]
	v_pk_add_f32 v[52:53], v[52:53], v[244:245]
	global_store_dwordx4 v[140:141], v[52:55], off offset:512
	global_load_dwordx4 v[244:247], v[252:253], off offset:512
	s_waitcnt vmcnt(6)
	v_pk_add_f32 v[50:51], v[50:51], v[250:251]
	v_pk_add_f32 v[48:49], v[48:49], v[248:249]
	global_store_dwordx4 v[140:141], v[48:51], off offset:528
	global_load_dwordx4 v[248:251], v[252:253], off offset:528
	s_waitcnt vmcnt(6)
	v_pk_add_f32 v[46:47], v[46:47], v[238:239]
	v_pk_add_f32 v[44:45], v[44:45], v[236:237]
	global_store_dwordx4 v[252:253], v[44:47], off offset:0
	s_mov_b64 s[0:1], 0x10000
	v_lshl_add_u64 v[140:141], v[252:253], 0, s[0:1]
	global_load_dwordx4 v[236:239], v[140:141], off offset:0
	s_waitcnt vmcnt(6)
	v_pk_add_f32 v[42:43], v[42:43], v[242:243]
	v_pk_add_f32 v[40:41], v[40:41], v[240:241]
	global_store_dwordx4 v[252:253], v[40:43], off offset:16
	global_load_dwordx4 v[240:243], v[140:141], off offset:16
	s_waitcnt vmcnt(6)
	v_pk_add_f32 v[38:39], v[38:39], v[246:247]
	v_pk_add_f32 v[36:37], v[36:37], v[244:245]
	global_store_dwordx4 v[252:253], v[36:39], off offset:512
	global_load_dwordx4 v[244:247], v[140:141], off offset:512
	s_waitcnt vmcnt(6)
	v_pk_add_f32 v[34:35], v[34:35], v[250:251]
	v_pk_add_f32 v[32:33], v[32:33], v[248:249]
	global_store_dwordx4 v[252:253], v[32:35], off offset:528
	global_load_dwordx4 v[248:251], v[140:141], off offset:528
	s_waitcnt vmcnt(6)
	v_pk_add_f32 v[30:31], v[30:31], v[238:239]
	v_pk_add_f32 v[28:29], v[28:29], v[236:237]
	global_store_dwordx4 v[140:141], v[28:31], off offset:0
	s_mov_b64 s[0:1], 0x10000
	v_lshl_add_u64 v[252:253], v[140:141], 0, s[0:1]
	global_load_dwordx4 v[236:239], v[252:253], off offset:0
	s_waitcnt vmcnt(6)
	v_pk_add_f32 v[26:27], v[26:27], v[242:243]
	v_pk_add_f32 v[24:25], v[24:25], v[240:241]
	global_store_dwordx4 v[140:141], v[24:27], off offset:16
	global_load_dwordx4 v[240:243], v[252:253], off offset:16
	s_waitcnt vmcnt(6)
	v_pk_add_f32 v[22:23], v[22:23], v[246:247]
	v_pk_add_f32 v[20:21], v[20:21], v[244:245]
	global_store_dwordx4 v[140:141], v[20:23], off offset:512
	global_load_dwordx4 v[244:247], v[252:253], off offset:512
	s_waitcnt vmcnt(6)
	v_pk_add_f32 v[18:19], v[18:19], v[250:251]
	v_pk_add_f32 v[16:17], v[16:17], v[248:249]
	global_store_dwordx4 v[140:141], v[16:19], off offset:528
	global_load_dwordx4 v[248:251], v[252:253], off offset:528
	s_waitcnt vmcnt(6)
	v_pk_add_f32 v[14:15], v[14:15], v[238:239]
	v_pk_add_f32 v[12:13], v[12:13], v[236:237]
	global_store_dwordx4 v[252:253], v[12:15], off offset:0
	s_waitcnt vmcnt(5)
	v_pk_add_f32 v[10:11], v[10:11], v[242:243]
	v_pk_add_f32 v[8:9], v[8:9], v[240:241]
	global_store_dwordx4 v[252:253], v[8:11], off offset:16
	s_waitcnt vmcnt(4)
	v_pk_add_f32 v[6:7], v[6:7], v[246:247]
	v_pk_add_f32 v[4:5], v[4:5], v[244:245]
	global_store_dwordx4 v[252:253], v[4:7], off offset:512
	s_waitcnt vmcnt(3)
	v_pk_add_f32 v[2:3], v[2:3], v[250:251]
	v_pk_add_f32 v[0:1], v[0:1], v[248:249]
	global_store_dwordx4 v[252:253], v[0:3], off offset:528
	s_mov_b64 s[0:1], -1
	s_and_b64 vcc, exec, s[8:9]
	s_cbranch_vccnz .LBB0_1000
	s_andn2_b64 vcc, exec, s[16:17]
	s_cbranch_vccnz .LBB0_999
	s_barrier
	s_branch .LBB0_999

.LBB0_1356:
	v_lshl_add_u32 v150, s24, 8, v143
	v_lshl_or_b32 v148, s50, 8, v153
	v_ashrrev_i32_e32 v151, 31, v150
	v_ashrrev_i32_e32 v149, 31, v148
	v_lshlrev_b64 v[140:141], 10, v[150:151]
	v_lshl_add_u64 v[140:141], v[140:141], 0, v[148:149]
	v_lshlrev_b64 v[140:141], 2, v[140:141]
	v_lshl_add_u64 v[160:161], s[12:13], 0, v[140:141]
	global_load_dwordx4 v[236:239], v140, s[12:13] offset:0
	global_load_dwordx4 v[240:243], v140, s[12:13] offset:16
	global_load_dwordx4 v[244:247], v140, s[12:13] offset:512
	global_load_dwordx4 v[248:251], v140, s[12:13] offset:528
	s_waitcnt vmcnt(3)
	v_pk_add_f32 v[128:129], v[128:129], v[238:239]
	v_pk_add_f32 v[126:127], v[126:127], v[236:237]
	global_store_dwordx4 v140, v[126:129], s[40:41] offset:0
	v_add_u32_e32 v252, 0x10000, v140
	global_load_dwordx4 v[236:239], v252, s[12:13] offset:0
	s_waitcnt vmcnt(4)
	v_pk_add_f32 v[124:125], v[124:125], v[242:243]
	v_pk_add_f32 v[122:123], v[122:123], v[240:241]
	global_store_dwordx4 v140, v[122:125], s[40:41] offset:16
	global_load_dwordx4 v[240:243], v252, s[12:13] offset:16
	s_waitcnt vmcnt(5)
	v_pk_add_f32 v[120:121], v[120:121], v[246:247]
	v_pk_add_f32 v[118:119], v[118:119], v[244:245]
	global_store_dwordx4 v140, v[118:121], s[40:41] offset:512
	global_load_dwordx4 v[244:247], v252, s[12:13] offset:512
	s_waitcnt vmcnt(6)
	v_pk_add_f32 v[116:117], v[116:117], v[250:251]
	v_pk_add_f32 v[114:115], v[114:115], v[248:249]
	global_store_dwordx4 v140, v[114:117], s[40:41] offset:528
	global_load_dwordx4 v[248:251], v252, s[12:13] offset:528
	s_waitcnt vmcnt(6)
	v_pk_add_f32 v[112:113], v[112:113], v[238:239]
	v_pk_add_f32 v[110:111], v[110:111], v[236:237]
	global_store_dwordx4 v252, v[110:113], s[40:41] offset:0
	v_add_u32_e32 v140, 0x10000, v252
	global_load_dwordx4 v[236:239], v140, s[12:13] offset:0
	s_waitcnt vmcnt(6)
	v_pk_add_f32 v[108:109], v[108:109], v[242:243]
	v_pk_add_f32 v[106:107], v[106:107], v[240:241]
	global_store_dwordx4 v252, v[106:109], s[40:41] offset:16
	global_load_dwordx4 v[240:243], v140, s[12:13] offset:16
	s_waitcnt vmcnt(6)
	v_pk_add_f32 v[104:105], v[104:105], v[246:247]
	v_pk_add_f32 v[102:103], v[102:103], v[244:245]
	global_store_dwordx4 v252, v[102:105], s[40:41] offset:512
	global_load_dwordx4 v[244:247], v140, s[12:13] offset:512
	s_waitcnt vmcnt(6)
	v_pk_add_f32 v[100:101], v[100:101], v[250:251]
	v_pk_add_f32 v[98:99], v[98:99], v[248:249]
	global_store_dwordx4 v252, v[98:101], s[40:41] offset:528
	global_load_dwordx4 v[248:251], v140, s[12:13] offset:528
	s_waitcnt vmcnt(6)
	v_pk_add_f32 v[96:97], v[96:97], v[238:239]
	v_pk_add_f32 v[94:95], v[94:95], v[236:237]
	global_store_dwordx4 v140, v[94:97], s[40:41] offset:0
	v_add_u32_e32 v252, 0x10000, v140
	global_load_dwordx4 v[236:239], v252, s[12:13] offset:0
	s_waitcnt vmcnt(6)
	v_pk_add_f32 v[92:93], v[92:93], v[242:243]
	v_pk_add_f32 v[90:91], v[90:91], v[240:241]
	global_store_dwordx4 v140, v[90:93], s[40:41] offset:16
	global_load_dwordx4 v[240:243], v252, s[12:13] offset:16
	s_waitcnt vmcnt(6)
	v_pk_add_f32 v[88:89], v[88:89], v[246:247]
	v_pk_add_f32 v[86:87], v[86:87], v[244:245]
	global_store_dwordx4 v140, v[86:89], s[40:41] offset:512
	global_load_dwordx4 v[244:247], v252, s[12:13] offset:512
	s_waitcnt vmcnt(6)
	v_pk_add_f32 v[84:85], v[84:85], v[250:251]
	v_pk_add_f32 v[82:83], v[82:83], v[248:249]
	global_store_dwordx4 v140, v[82:85], s[40:41] offset:528
	global_load_dwordx4 v[248:251], v252, s[12:13] offset:528
	s_waitcnt vmcnt(6)
	v_pk_add_f32 v[80:81], v[80:81], v[238:239]
	v_pk_add_f32 v[78:79], v[78:79], v[236:237]
	global_store_dwordx4 v252, v[78:81], s[40:41] offset:0
	v_add_u32_e32 v140, 0x50000, v252
	global_load_dwordx4 v[236:239], v140, s[12:13] offset:0
	s_waitcnt vmcnt(6)
	v_pk_add_f32 v[76:77], v[76:77], v[242:243]
	v_pk_add_f32 v[74:75], v[74:75], v[240:241]
	global_store_dwordx4 v252, v[74:77], s[40:41] offset:16
	global_load_dwordx4 v[240:243], v140, s[12:13] offset:16
	s_waitcnt vmcnt(6)
	v_pk_add_f32 v[72:73], v[72:73], v[246:247]
	v_pk_add_f32 v[70:71], v[70:71], v[244:245]
	global_store_dwordx4 v252, v[70:73], s[40:41] offset:512
	global_load_dwordx4 v[244:247], v140, s[12:13] offset:512
	s_waitcnt vmcnt(6)
	v_pk_add_f32 v[68:69], v[68:69], v[250:251]
	v_pk_add_f32 v[66:67], v[66:67], v[248:249]
	global_store_dwordx4 v252, v[66:69], s[40:41] offset:528
	global_load_dwordx4 v[248:251], v140, s[12:13] offset:528
	s_waitcnt vmcnt(6)
	v_pk_add_f32 v[62:63], v[62:63], v[238:239]
	v_pk_add_f32 v[60:61], v[60:61], v[236:237]
	global_store_dwordx4 v140, v[60:63], s[40:41] offset:0
	v_add_u32_e32 v252, 0x10000, v140
	global_load_dwordx4 v[236:239], v252, s[12:13] offset:0
	s_waitcnt vmcnt(6)
	v_pk_add_f32 v[58:59], v[58:59], v[242:243]
	v_pk_add_f32 v[56:57], v[56:57], v[240:241]
	global_store_dwordx4 v140, v[56:59], s[40:41] offset:16
	global_load_dwordx4 v[240:243], v252, s[12:13] offset:16
	s_waitcnt vmcnt(6)
	v_pk_add_f32 v[54:55], v[54:55], v[246:247]
	v_pk_add_f32 v[52:53], v[52:53], v[244:245]
	global_store_dwordx4 v140, v[52:55], s[40:41] offset:512
	global_load_dwordx4 v[244:247], v252, s[12:13] offset:512
	s_waitcnt vmcnt(6)
	v_pk_add_f32 v[50:51], v[50:51], v[250:251]
	v_pk_add_f32 v[48:49], v[48:49], v[248:249]
	global_store_dwordx4 v140, v[48:51], s[40:41] offset:528
	global_load_dwordx4 v[248:251], v252, s[12:13] offset:528
	s_waitcnt vmcnt(6)
	v_pk_add_f32 v[46:47], v[46:47], v[238:239]
	v_pk_add_f32 v[44:45], v[44:45], v[236:237]
	global_store_dwordx4 v252, v[44:47], s[40:41] offset:0
	v_add_u32_e32 v140, 0x10000, v252
	global_load_dwordx4 v[236:239], v140, s[12:13] offset:0
	s_waitcnt vmcnt(6)
	v_pk_add_f32 v[42:43], v[42:43], v[242:243]
	v_pk_add_f32 v[40:41], v[40:41], v[240:241]
	global_store_dwordx4 v252, v[40:43], s[40:41] offset:16
	global_load_dwordx4 v[240:243], v140, s[12:13] offset:16
	s_waitcnt vmcnt(6)
	v_pk_add_f32 v[38:39], v[38:39], v[246:247]
	v_pk_add_f32 v[36:37], v[36:37], v[244:245]
	global_store_dwordx4 v252, v[36:39], s[40:41] offset:512
	global_load_dwordx4 v[244:247], v140, s[12:13] offset:512
	s_waitcnt vmcnt(6)
	v_pk_add_f32 v[34:35], v[34:35], v[250:251]
	v_pk_add_f32 v[32:33], v[32:33], v[248:249]
	global_store_dwordx4 v252, v[32:35], s[40:41] offset:528
	global_load_dwordx4 v[248:251], v140, s[12:13] offset:528
	s_waitcnt vmcnt(6)
	v_pk_add_f32 v[30:31], v[30:31], v[238:239]
	v_pk_add_f32 v[28:29], v[28:29], v[236:237]
	global_store_dwordx4 v140, v[28:31], s[40:41] offset:0
	v_add_u32_e32 v252, 0x10000, v140
	global_load_dwordx4 v[236:239], v252, s[12:13] offset:0
	s_waitcnt vmcnt(6)
	v_pk_add_f32 v[26:27], v[26:27], v[242:243]
	v_pk_add_f32 v[24:25], v[24:25], v[240:241]
	global_store_dwordx4 v140, v[24:27], s[40:41] offset:16
	global_load_dwordx4 v[240:243], v252, s[12:13] offset:16
	s_waitcnt vmcnt(6)
	v_pk_add_f32 v[22:23], v[22:23], v[246:247]
	v_pk_add_f32 v[20:21], v[20:21], v[244:245]
	global_store_dwordx4 v140, v[20:23], s[40:41] offset:512
	global_load_dwordx4 v[244:247], v252, s[12:13] offset:512
	s_waitcnt vmcnt(6)
	v_pk_add_f32 v[18:19], v[18:19], v[250:251]
	v_pk_add_f32 v[16:17], v[16:17], v[248:249]
	global_store_dwordx4 v140, v[16:19], s[40:41] offset:528
	global_load_dwordx4 v[248:251], v252, s[12:13] offset:528
	s_waitcnt vmcnt(6)
	v_pk_add_f32 v[14:15], v[14:15], v[238:239]
	v_pk_add_f32 v[12:13], v[12:13], v[236:237]
	global_store_dwordx4 v252, v[12:15], s[40:41] offset:0
	s_waitcnt vmcnt(5)
	v_pk_add_f32 v[10:11], v[10:11], v[242:243]
	v_pk_add_f32 v[8:9], v[8:9], v[240:241]
	global_store_dwordx4 v252, v[8:11], s[40:41] offset:16
	s_waitcnt vmcnt(4)
	v_pk_add_f32 v[6:7], v[6:7], v[246:247]
	v_pk_add_f32 v[4:5], v[4:5], v[244:245]
	global_store_dwordx4 v252, v[4:7], s[40:41] offset:512
	s_waitcnt vmcnt(3)
	v_pk_add_f32 v[2:3], v[2:3], v[250:251]
	v_pk_add_f32 v[0:1], v[0:1], v[248:249]
	global_store_dwordx4 v252, v[0:3], s[40:41] offset:528
	s_mov_b64 s[0:1], -1
	s_andn2_b64 vcc, exec, s[8:9]
	s_cbranch_vccnz .LBB0_1345
	s_andn2_b64 vcc, exec, s[10:11]
	s_cbranch_vccnz .LBB0_1344
	s_barrier
	s_branch .LBB0_1344

.LBB0_1582:
	v_lshl_add_u32 v150, s37, 8, v143
	v_lshl_or_b32 v140, s38, 8, v153
	v_ashrrev_i32_e32 v151, 31, v150
	v_ashrrev_i32_e32 v141, 31, v140
	v_lshlrev_b64 v[144:145], 12, v[150:151]
	v_lshl_add_u64 v[144:145], s[40:41], 0, v[144:145]
	v_lshlrev_b64 v[148:149], 2, v[140:141]
	v_lshl_add_u64 v[140:141], v[144:145], 0, v[148:149]
	global_load_dwordx4 v[236:239], v[140:141], off offset:0
	global_load_dwordx4 v[240:243], v[140:141], off offset:16
	global_load_dwordx4 v[244:247], v[140:141], off offset:512
	global_load_dwordx4 v[248:251], v[140:141], off offset:528
	s_waitcnt vmcnt(3)
	v_pk_add_f32 v[128:129], v[128:129], v[238:239]
	v_pk_add_f32 v[126:127], v[126:127], v[236:237]
	global_store_dwordx4 v[140:141], v[126:129], off offset:0
	s_mov_b64 s[0:1], 0x10000
	v_lshl_add_u64 v[252:253], v[140:141], 0, s[0:1]
	global_load_dwordx4 v[236:239], v[252:253], off offset:0
	s_waitcnt vmcnt(4)
	v_pk_add_f32 v[124:125], v[124:125], v[242:243]
	v_pk_add_f32 v[122:123], v[122:123], v[240:241]
	global_store_dwordx4 v[140:141], v[122:125], off offset:16
	global_load_dwordx4 v[240:243], v[252:253], off offset:16
	s_waitcnt vmcnt(5)
	v_pk_add_f32 v[120:121], v[120:121], v[246:247]
	v_pk_add_f32 v[118:119], v[118:119], v[244:245]
	global_store_dwordx4 v[140:141], v[118:121], off offset:512
	global_load_dwordx4 v[244:247], v[252:253], off offset:512
	s_waitcnt vmcnt(6)
	v_pk_add_f32 v[116:117], v[116:117], v[250:251]
	v_pk_add_f32 v[114:115], v[114:115], v[248:249]
	global_store_dwordx4 v[140:141], v[114:117], off offset:528
	global_load_dwordx4 v[248:251], v[252:253], off offset:528
	s_waitcnt vmcnt(6)
	v_pk_add_f32 v[112:113], v[112:113], v[238:239]
	v_pk_add_f32 v[110:111], v[110:111], v[236:237]
	global_store_dwordx4 v[252:253], v[110:113], off offset:0
	s_mov_b64 s[0:1], 0x10000
	v_lshl_add_u64 v[140:141], v[252:253], 0, s[0:1]
	global_load_dwordx4 v[236:239], v[140:141], off offset:0
	s_waitcnt vmcnt(6)
	v_pk_add_f32 v[108:109], v[108:109], v[242:243]
	v_pk_add_f32 v[106:107], v[106:107], v[240:241]
	global_store_dwordx4 v[252:253], v[106:109], off offset:16
	global_load_dwordx4 v[240:243], v[140:141], off offset:16
	s_waitcnt vmcnt(6)
	v_pk_add_f32 v[104:105], v[104:105], v[246:247]
	v_pk_add_f32 v[102:103], v[102:103], v[244:245]
	global_store_dwordx4 v[252:253], v[102:105], off offset:512
	global_load_dwordx4 v[244:247], v[140:141], off offset:512
	s_waitcnt vmcnt(6)
	v_pk_add_f32 v[100:101], v[100:101], v[250:251]
	v_pk_add_f32 v[98:99], v[98:99], v[248:249]
	global_store_dwordx4 v[252:253], v[98:101], off offset:528
	global_load_dwordx4 v[248:251], v[140:141], off offset:528
	s_waitcnt vmcnt(6)
	v_pk_add_f32 v[96:97], v[96:97], v[238:239]
	v_pk_add_f32 v[94:95], v[94:95], v[236:237]
	global_store_dwordx4 v[140:141], v[94:97], off offset:0
	s_mov_b64 s[0:1], 0x10000
	v_lshl_add_u64 v[252:253], v[140:141], 0, s[0:1]
	global_load_dwordx4 v[236:239], v[252:253], off offset:0
	s_waitcnt vmcnt(6)
	v_pk_add_f32 v[92:93], v[92:93], v[242:243]
	v_pk_add_f32 v[90:91], v[90:91], v[240:241]
	global_store_dwordx4 v[140:141], v[90:93], off offset:16
	global_load_dwordx4 v[240:243], v[252:253], off offset:16
	s_waitcnt vmcnt(6)
	v_pk_add_f32 v[88:89], v[88:89], v[246:247]
	v_pk_add_f32 v[86:87], v[86:87], v[244:245]
	global_store_dwordx4 v[140:141], v[86:89], off offset:512
	global_load_dwordx4 v[244:247], v[252:253], off offset:512
	s_waitcnt vmcnt(6)
	v_pk_add_f32 v[84:85], v[84:85], v[250:251]
	v_pk_add_f32 v[82:83], v[82:83], v[248:249]
	global_store_dwordx4 v[140:141], v[82:85], off offset:528
	global_load_dwordx4 v[248:251], v[252:253], off offset:528
	s_waitcnt vmcnt(6)
	v_pk_add_f32 v[80:81], v[80:81], v[238:239]
	v_pk_add_f32 v[78:79], v[78:79], v[236:237]
	global_store_dwordx4 v[252:253], v[78:81], off offset:0
	s_mov_b64 s[0:1], 0x50000
	v_lshl_add_u64 v[140:141], v[252:253], 0, s[0:1]
	global_load_dwordx4 v[236:239], v[140:141], off offset:0
	s_waitcnt vmcnt(6)
	v_pk_add_f32 v[76:77], v[76:77], v[242:243]
	v_pk_add_f32 v[74:75], v[74:75], v[240:241]
	global_store_dwordx4 v[252:253], v[74:77], off offset:16
	global_load_dwordx4 v[240:243], v[140:141], off offset:16
	s_waitcnt vmcnt(6)
	v_pk_add_f32 v[72:73], v[72:73], v[246:247]
	v_pk_add_f32 v[70:71], v[70:71], v[244:245]
	global_store_dwordx4 v[252:253], v[70:73], off offset:512
	global_load_dwordx4 v[244:247], v[140:141], off offset:512
	s_waitcnt vmcnt(6)
	v_pk_add_f32 v[68:69], v[68:69], v[250:251]
	v_pk_add_f32 v[66:67], v[66:67], v[248:249]
	global_store_dwordx4 v[252:253], v[66:69], off offset:528
	global_load_dwordx4 v[248:251], v[140:141], off offset:528
	s_waitcnt vmcnt(6)
	v_pk_add_f32 v[62:63], v[62:63], v[238:239]
	v_pk_add_f32 v[60:61], v[60:61], v[236:237]
	global_store_dwordx4 v[140:141], v[60:63], off offset:0
	s_mov_b64 s[0:1], 0x10000
	v_lshl_add_u64 v[252:253], v[140:141], 0, s[0:1]
	global_load_dwordx4 v[236:239], v[252:253], off offset:0
	s_waitcnt vmcnt(6)
	v_pk_add_f32 v[58:59], v[58:59], v[242:243]
	v_pk_add_f32 v[56:57], v[56:57], v[240:241]
	global_store_dwordx4 v[140:141], v[56:59], off offset:16
	global_load_dwordx4 v[240:243], v[252:253], off offset:16
	s_waitcnt vmcnt(6)
	v_pk_add_f32 v[54:55], v[54:55], v[246:247]
	v_pk_add_f32 v[52:53], v[52:53], v[244:245]
	global_store_dwordx4 v[140:141], v[52:55], off offset:512
	global_load_dwordx4 v[244:247], v[252:253], off offset:512
	s_waitcnt vmcnt(6)
	v_pk_add_f32 v[50:51], v[50:51], v[250:251]
	v_pk_add_f32 v[48:49], v[48:49], v[248:249]
	global_store_dwordx4 v[140:141], v[48:51], off offset:528
	global_load_dwordx4 v[248:251], v[252:253], off offset:528
	s_waitcnt vmcnt(6)
	v_pk_add_f32 v[46:47], v[46:47], v[238:239]
	v_pk_add_f32 v[44:45], v[44:45], v[236:237]
	global_store_dwordx4 v[252:253], v[44:47], off offset:0
	s_mov_b64 s[0:1], 0x10000
	v_lshl_add_u64 v[140:141], v[252:253], 0, s[0:1]
	global_load_dwordx4 v[236:239], v[140:141], off offset:0
	s_waitcnt vmcnt(6)
	v_pk_add_f32 v[42:43], v[42:43], v[242:243]
	v_pk_add_f32 v[40:41], v[40:41], v[240:241]
	global_store_dwordx4 v[252:253], v[40:43], off offset:16
	global_load_dwordx4 v[240:243], v[140:141], off offset:16
	s_waitcnt vmcnt(6)
	v_pk_add_f32 v[38:39], v[38:39], v[246:247]
	v_pk_add_f32 v[36:37], v[36:37], v[244:245]
	global_store_dwordx4 v[252:253], v[36:39], off offset:512
	global_load_dwordx4 v[244:247], v[140:141], off offset:512
	s_waitcnt vmcnt(6)
	v_pk_add_f32 v[34:35], v[34:35], v[250:251]
	v_pk_add_f32 v[32:33], v[32:33], v[248:249]
	global_store_dwordx4 v[252:253], v[32:35], off offset:528
	global_load_dwordx4 v[248:251], v[140:141], off offset:528
	s_waitcnt vmcnt(6)
	v_pk_add_f32 v[30:31], v[30:31], v[238:239]
	v_pk_add_f32 v[28:29], v[28:29], v[236:237]
	global_store_dwordx4 v[140:141], v[28:31], off offset:0
	s_mov_b64 s[0:1], 0x10000
	v_lshl_add_u64 v[252:253], v[140:141], 0, s[0:1]
	global_load_dwordx4 v[236:239], v[252:253], off offset:0
	s_waitcnt vmcnt(6)
	v_pk_add_f32 v[26:27], v[26:27], v[242:243]
	v_pk_add_f32 v[24:25], v[24:25], v[240:241]
	global_store_dwordx4 v[140:141], v[24:27], off offset:16
	global_load_dwordx4 v[240:243], v[252:253], off offset:16
	s_waitcnt vmcnt(6)
	v_pk_add_f32 v[22:23], v[22:23], v[246:247]
	v_pk_add_f32 v[20:21], v[20:21], v[244:245]
	global_store_dwordx4 v[140:141], v[20:23], off offset:512
	global_load_dwordx4 v[244:247], v[252:253], off offset:512
	s_waitcnt vmcnt(6)
	v_pk_add_f32 v[18:19], v[18:19], v[250:251]
	v_pk_add_f32 v[16:17], v[16:17], v[248:249]
	global_store_dwordx4 v[140:141], v[16:19], off offset:528
	global_load_dwordx4 v[248:251], v[252:253], off offset:528
	s_waitcnt vmcnt(6)
	v_pk_add_f32 v[14:15], v[14:15], v[238:239]
	v_pk_add_f32 v[12:13], v[12:13], v[236:237]
	global_store_dwordx4 v[252:253], v[12:15], off offset:0
	s_waitcnt vmcnt(5)
	v_pk_add_f32 v[10:11], v[10:11], v[242:243]
	v_pk_add_f32 v[8:9], v[8:9], v[240:241]
	global_store_dwordx4 v[252:253], v[8:11], off offset:16
	s_waitcnt vmcnt(4)
	v_pk_add_f32 v[6:7], v[6:7], v[246:247]
	v_pk_add_f32 v[4:5], v[4:5], v[244:245]
	global_store_dwordx4 v[252:253], v[4:7], off offset:512
	s_waitcnt vmcnt(3)
	v_pk_add_f32 v[2:3], v[2:3], v[250:251]
	v_pk_add_f32 v[0:1], v[0:1], v[248:249]
	global_store_dwordx4 v[252:253], v[0:3], off offset:528
	s_mov_b64 s[0:1], -1
	s_and_b64 vcc, exec, s[8:9]
	s_cbranch_vccnz .LBB0_1567
	s_andn2_b64 vcc, exec, s[12:13]
	s_cbranch_vccnz .LBB0_1566
	s_barrier
	s_branch .LBB0_1566
